# grid barrier: XCD leader bumps the XCD generation before invalidating its own L1
# baseline (speedup 1.0000x reference)
; __device__ __forceinline__ unsigned xb_add(unsigned* p, unsigned v) { return __hip_atomic_fetch_add(p, v, __ATOMIC_RELAXED, __HIP_MEMORY_SCOPE_AGENT); }
; __device__ __forceinline__ void xcd_barrier(const XcdBarrier& b) {
;     ...
;             __builtin_amdgcn_fence(__ATOMIC_ACQUIRE, "agent");
;             xb_add(&bar[XB_XGEN(b.x)], 1u);
;             asm volatile("s_waitcnt vmcnt(0)" ::: "memory");
.LBB0_137:
	s_or_b64 exec, exec, s[10:11]
	s_mov_b64 s[10:11], exec
	v_mbcnt_lo_u32_b32 v0, s10, 0
	v_mbcnt_hi_u32_b32 v0, s11, v0
	v_cmp_eq_u32_e32 vcc, 0, v0
	s_waitcnt vmcnt(0)
	s_and_saveexec_b64 s[14:15], vcc
	s_cbranch_execz .LBB0_139
	s_bcnt1_i32_b64 s4, s[10:11]
	v_mov_b32_e32 v0, s4
	global_atomic_add v1, v0, s[58:59]
.LBB0_139:
	s_or_b64 exec, exec, s[14:15]
	buffer_inv sc1
	s_waitcnt vmcnt(0)
